# dropped the duplicate accumulator zero-init at every GEMM unit header (128 v_mov per tile per wave; the K-loop entry already zeroes them)
# speedup vs baseline: 1.0290x; 1.0090x over previous
; template <class Epi, class Sched, bool ALIGN_EPI = false, bool SP2 = false>
; __device__ __forceinline__ void gemm_phase(PG8_LAS unsigned char* lds, const Gemm g, const Sched& S, const Epi& E) {
;     ...
;     f32x4 acc[2][2][4][2];
; #pragma unroll
;     for (int a = 0; a < 2; ++a)
; #pragma unroll
;         for (int b = 0; b < 2; ++b)
; #pragma unroll
;             for (int m = 0; m < 4; ++m)
; #pragma unroll
;                 for (int n = 0; n < 2; ++n) acc[a][b][m][n] = (f32x4){0.f, 0.f, 0.f, 0.f};
;     ...
; #pragma unroll
;         for (int a = 0; a < 2; ++a)
; #pragma unroll
;             for (int b = 0; b < 2; ++b)
; #pragma unroll
;                 for (int m = 0; m < 4; ++m)
; #pragma unroll
;                     for (int n = 0; n < 2; ++n) acc[a][b][m][n] = (f32x4){0.f, 0.f, 0.f, 0.f};
.LBB0_371:
	s_andn2_b64 vcc, exec, s[14:15]
	s_cbranch_vccnz .LBB0_374
	s_add_u32 s24, s24, 0x80
	s_addc_u32 s25, s25, 0
	s_add_u32 s62, s26, 0x100
	v_mov_b32_e32 v8, 0
	s_addc_u32 s63, s27, 0
	s_mov_b32 s26, 0
	v_mov_b32_e32 v9, v8
	v_mov_b32_e32 v10, v8
	v_mov_b32_e32 v11, v8
	v_mov_b32_e32 v12, v8
	v_mov_b32_e32 v13, v8
	v_mov_b32_e32 v14, v8
	v_mov_b32_e32 v15, v8
	v_mov_b32_e32 v24, v8
	v_mov_b32_e32 v25, v8
	v_mov_b32_e32 v26, v8
	v_mov_b32_e32 v27, v8
	v_mov_b32_e32 v28, v8
	v_mov_b32_e32 v29, v8
	v_mov_b32_e32 v30, v8
	v_mov_b32_e32 v31, v8
	v_mov_b32_e32 v40, v8
	v_mov_b32_e32 v41, v8
	v_mov_b32_e32 v42, v8
	v_mov_b32_e32 v43, v8
	v_mov_b32_e32 v44, v8
	v_mov_b32_e32 v45, v8
	v_mov_b32_e32 v46, v8
	v_mov_b32_e32 v47, v8
	v_mov_b32_e32 v56, v8
	v_mov_b32_e32 v57, v8
	v_mov_b32_e32 v58, v8
	v_mov_b32_e32 v59, v8
	v_mov_b32_e32 v60, v8
	v_mov_b32_e32 v61, v8
	v_mov_b32_e32 v62, v8
	v_mov_b32_e32 v63, v8
	v_mov_b32_e32 v0, v8
	v_mov_b32_e32 v1, v8
	v_mov_b32_e32 v2, v8
	v_mov_b32_e32 v3, v8
	v_mov_b32_e32 v4, v8
	v_mov_b32_e32 v5, v8
	v_mov_b32_e32 v6, v8
	v_mov_b32_e32 v7, v8
	v_mov_b32_e32 v16, v8
	v_mov_b32_e32 v17, v8
	v_mov_b32_e32 v18, v8
	v_mov_b32_e32 v19, v8
	v_mov_b32_e32 v20, v8
	v_mov_b32_e32 v21, v8
	v_mov_b32_e32 v22, v8
	v_mov_b32_e32 v23, v8
	v_mov_b32_e32 v32, v8
	v_mov_b32_e32 v33, v8
	v_mov_b32_e32 v34, v8
	v_mov_b32_e32 v35, v8
	v_mov_b32_e32 v36, v8
	v_mov_b32_e32 v37, v8
	v_mov_b32_e32 v38, v8
	v_mov_b32_e32 v39, v8
	v_mov_b32_e32 v48, v8
	v_mov_b32_e32 v49, v8
	v_mov_b32_e32 v50, v8
	v_mov_b32_e32 v51, v8
	v_mov_b32_e32 v52, v8
	v_mov_b32_e32 v53, v8
	v_mov_b32_e32 v54, v8
	v_mov_b32_e32 v55, v8
	v_mov_b32_e32 v72, v8
	v_mov_b32_e32 v73, v8
	v_mov_b32_e32 v74, v8
	v_mov_b32_e32 v75, v8
	v_mov_b32_e32 v76, v8
	v_mov_b32_e32 v77, v8
	v_mov_b32_e32 v78, v8
	v_mov_b32_e32 v79, v8
	v_mov_b32_e32 v88, v8
	v_mov_b32_e32 v89, v8
	v_mov_b32_e32 v90, v8
	v_mov_b32_e32 v91, v8
	v_mov_b32_e32 v92, v8
	v_mov_b32_e32 v93, v8
	v_mov_b32_e32 v94, v8
	v_mov_b32_e32 v95, v8
	v_mov_b32_e32 v104, v8
	v_mov_b32_e32 v105, v8
	v_mov_b32_e32 v106, v8
	v_mov_b32_e32 v107, v8
	v_mov_b32_e32 v108, v8
	v_mov_b32_e32 v109, v8
	v_mov_b32_e32 v110, v8
	v_mov_b32_e32 v111, v8
	v_mov_b32_e32 v120, v8
	v_mov_b32_e32 v121, v8
	v_mov_b32_e32 v122, v8
	v_mov_b32_e32 v123, v8
	v_mov_b32_e32 v124, v8
	v_mov_b32_e32 v125, v8
	v_mov_b32_e32 v126, v8
	v_mov_b32_e32 v127, v8
	v_mov_b32_e32 v64, v8
	v_mov_b32_e32 v65, v8
	v_mov_b32_e32 v66, v8
	v_mov_b32_e32 v67, v8
	v_mov_b32_e32 v68, v8
	v_mov_b32_e32 v69, v8
	v_mov_b32_e32 v70, v8
	v_mov_b32_e32 v71, v8
	v_mov_b32_e32 v80, v8
	v_mov_b32_e32 v81, v8
	v_mov_b32_e32 v82, v8
	v_mov_b32_e32 v83, v8
	v_mov_b32_e32 v84, v8
	v_mov_b32_e32 v85, v8
	v_mov_b32_e32 v86, v8
	v_mov_b32_e32 v87, v8
	v_mov_b32_e32 v96, v8
	v_mov_b32_e32 v97, v8
	v_mov_b32_e32 v98, v8
	v_mov_b32_e32 v99, v8
	v_mov_b32_e32 v100, v8
	v_mov_b32_e32 v101, v8
	v_mov_b32_e32 v102, v8
	v_mov_b32_e32 v103, v8
	v_mov_b32_e32 v112, v8
	v_mov_b32_e32 v113, v8
	v_mov_b32_e32 v114, v8
	v_mov_b32_e32 v115, v8
	v_mov_b32_e32 v116, v8
	v_mov_b32_e32 v117, v8
	v_mov_b32_e32 v118, v8
	v_mov_b32_e32 v119, v8

; template <class Epi, class Sched, bool ALIGN_EPI = false, bool SP2 = false>
; __device__ __forceinline__ void gemm_phase(PG8_LAS unsigned char* lds, const Gemm g, const Sched& S, const Epi& E) {
;     ...
;         for (int t = 0; t < nt; t += 2) {
;             const bool last = (t == nt - 2);
;             const char* a1 = cA + (size_t)(t + 1) * kstep;
;     ...
; #pragma unroll
;         for (int a = 0; a < 2; ++a)
; #pragma unroll
;             for (int b = 0; b < 2; ++b)
; #pragma unroll
;                 for (int m = 0; m < 4; ++m)
; #pragma unroll
;                     for (int n = 0; n < 2; ++n) acc[a][b][m][n] = (f32x4){0.f, 0.f, 0.f, 0.f};
.LBB0_465:
	v_mov_b32_e32 v151, 0
	s_andn2_b64 vcc, exec, s[24:25]
	v_mov_b32_e32 v150, 0
	v_mov_b32_e32 v155, 0
	v_mov_b32_e32 v154, 0
	v_mov_b32_e32 v153, 0
	v_mov_b32_e32 v152, 0
	v_mov_b32_e32 v149, 0
	v_mov_b32_e32 v148, 0
	v_mov_b32_e32 v145, 0
	v_mov_b32_e32 v144, 0
	v_mov_b32_e32 v147, 0
	v_mov_b32_e32 v146, 0
	s_waitcnt lgkmcnt(0)
	s_cbranch_vccnz .LBB0_469
	s_add_u32 s30, s30, 0x80
	s_addc_u32 s31, s31, 0
	s_add_u32 s65, s34, 0x100
	v_mov_b32_e32 v0, 0
	s_addc_u32 s66, s35, 0
	s_mov_b32 s34, 0
	v_mov_b32_e32 v1, v0
	v_mov_b32_e32 v2, v0
	v_mov_b32_e32 v3, v0
	v_mov_b32_e32 v4, v0
	v_mov_b32_e32 v5, v0
	v_mov_b32_e32 v6, v0
	v_mov_b32_e32 v7, v0
	v_mov_b32_e32 v8, v0
	v_mov_b32_e32 v9, v0
	v_mov_b32_e32 v10, v0
	v_mov_b32_e32 v11, v0
	v_mov_b32_e32 v12, v0
	v_mov_b32_e32 v13, v0
	v_mov_b32_e32 v14, v0
	v_mov_b32_e32 v15, v0
	v_mov_b32_e32 v20, v0
	v_mov_b32_e32 v21, v0
	v_mov_b32_e32 v22, v0
	v_mov_b32_e32 v23, v0
	v_mov_b32_e32 v28, v0
	v_mov_b32_e32 v29, v0
	v_mov_b32_e32 v30, v0
	v_mov_b32_e32 v31, v0
	v_mov_b32_e32 v36, v0
	v_mov_b32_e32 v37, v0
	v_mov_b32_e32 v38, v0
	v_mov_b32_e32 v39, v0
	v_mov_b32_e32 v44, v0
	v_mov_b32_e32 v45, v0
	v_mov_b32_e32 v46, v0
	v_mov_b32_e32 v47, v0
	v_mov_b32_e32 v16, v0
	v_mov_b32_e32 v17, v0
	v_mov_b32_e32 v18, v0
	v_mov_b32_e32 v19, v0
	v_mov_b32_e32 v24, v0
	v_mov_b32_e32 v25, v0
	v_mov_b32_e32 v26, v0
	v_mov_b32_e32 v27, v0
	v_mov_b32_e32 v32, v0
	v_mov_b32_e32 v33, v0
	v_mov_b32_e32 v34, v0
	v_mov_b32_e32 v35, v0
	v_mov_b32_e32 v40, v0
	v_mov_b32_e32 v41, v0
	v_mov_b32_e32 v42, v0
	v_mov_b32_e32 v43, v0
	v_mov_b32_e32 v48, v0
	v_mov_b32_e32 v49, v0
	v_mov_b32_e32 v50, v0
	v_mov_b32_e32 v51, v0
	v_mov_b32_e32 v52, v0
	v_mov_b32_e32 v53, v0
	v_mov_b32_e32 v54, v0
	v_mov_b32_e32 v55, v0
	v_mov_b32_e32 v56, v0
	v_mov_b32_e32 v57, v0
	v_mov_b32_e32 v58, v0
	v_mov_b32_e32 v59, v0
	v_mov_b32_e32 v60, v0
	v_mov_b32_e32 v61, v0
	v_mov_b32_e32 v62, v0
	v_mov_b32_e32 v63, v0
	v_mov_b32_e32 v64, v0
	v_mov_b32_e32 v65, v0
	v_mov_b32_e32 v66, v0
	v_mov_b32_e32 v67, v0
	v_mov_b32_e32 v68, v0
	v_mov_b32_e32 v69, v0
	v_mov_b32_e32 v70, v0
	v_mov_b32_e32 v71, v0
	v_mov_b32_e32 v72, v0
	v_mov_b32_e32 v73, v0
	v_mov_b32_e32 v74, v0
	v_mov_b32_e32 v75, v0
	v_mov_b32_e32 v76, v0
	v_mov_b32_e32 v77, v0
	v_mov_b32_e32 v78, v0
	v_mov_b32_e32 v79, v0
	v_mov_b32_e32 v84, v0
	v_mov_b32_e32 v85, v0
	v_mov_b32_e32 v86, v0
	v_mov_b32_e32 v87, v0
	v_mov_b32_e32 v92, v0
	v_mov_b32_e32 v93, v0
	v_mov_b32_e32 v94, v0
	v_mov_b32_e32 v95, v0
	v_mov_b32_e32 v100, v0
	v_mov_b32_e32 v101, v0
	v_mov_b32_e32 v102, v0
	v_mov_b32_e32 v103, v0
	v_mov_b32_e32 v108, v0
	v_mov_b32_e32 v109, v0
	v_mov_b32_e32 v110, v0
	v_mov_b32_e32 v111, v0
	v_mov_b32_e32 v80, v0
	v_mov_b32_e32 v81, v0
	v_mov_b32_e32 v82, v0
	v_mov_b32_e32 v83, v0
	v_mov_b32_e32 v88, v0
	v_mov_b32_e32 v89, v0
	v_mov_b32_e32 v90, v0
	v_mov_b32_e32 v91, v0
	v_mov_b32_e32 v96, v0
	v_mov_b32_e32 v97, v0
	v_mov_b32_e32 v98, v0
	v_mov_b32_e32 v99, v0
	v_mov_b32_e32 v104, v0
	v_mov_b32_e32 v105, v0
	v_mov_b32_e32 v106, v0
	v_mov_b32_e32 v107, v0
	v_mov_b32_e32 v112, v0
	v_mov_b32_e32 v113, v0
	v_mov_b32_e32 v114, v0
	v_mov_b32_e32 v115, v0
	v_mov_b32_e32 v116, v0
	v_mov_b32_e32 v117, v0
	v_mov_b32_e32 v118, v0
	v_mov_b32_e32 v119, v0
	v_mov_b32_e32 v120, v0
	v_mov_b32_e32 v121, v0
	v_mov_b32_e32 v122, v0
	v_mov_b32_e32 v123, v0
	v_mov_b32_e32 v124, v0
	v_mov_b32_e32 v125, v0
	v_mov_b32_e32 v126, v0
	v_mov_b32_e32 v127, v0

; template <class Epi, class Sched, bool ALIGN_EPI = false, bool SP2 = false>
; __device__ __forceinline__ void gemm_phase(PG8_LAS unsigned char* lds, const Gemm g, const Sched& S, const Epi& E) {
;     ...
;         for (int t = 0; t < nt; t += 2) {
;             const bool last = (t == nt - 2);
;             const char* a1 = cA + (size_t)(t + 1) * kstep;
;     ...
; #pragma unroll
;         for (int a = 0; a < 2; ++a)
; #pragma unroll
;             for (int b = 0; b < 2; ++b)
; #pragma unroll
;                 for (int m = 0; m < 4; ++m)
; #pragma unroll
;                     for (int n = 0; n < 2; ++n) acc[a][b][m][n] = (f32x4){0.f, 0.f, 0.f, 0.f};
.LBB0_595:
	s_andn2_b64 vcc, exec, s[78:79]
	s_cbranch_vccnz .LBB0_598
	s_add_u32 s4, s4, 0x80
	s_addc_u32 s5, s5, 0
	s_add_u32 s9, s6, 0x100
	v_mov_b32_e32 v0, 0
	s_addc_u32 s27, s7, 0
	s_mov_b32 s6, 0
	v_mov_b32_e32 v1, v0
	v_mov_b32_e32 v2, v0
	v_mov_b32_e32 v3, v0
	v_mov_b32_e32 v4, v0
	v_mov_b32_e32 v5, v0
	v_mov_b32_e32 v6, v0
	v_mov_b32_e32 v7, v0
	v_mov_b32_e32 v16, v0
	v_mov_b32_e32 v17, v0
	v_mov_b32_e32 v18, v0
	v_mov_b32_e32 v19, v0
	v_mov_b32_e32 v20, v0
	v_mov_b32_e32 v21, v0
	v_mov_b32_e32 v22, v0
	v_mov_b32_e32 v23, v0
	v_mov_b32_e32 v32, v0
	v_mov_b32_e32 v33, v0
	v_mov_b32_e32 v34, v0
	v_mov_b32_e32 v35, v0
	v_mov_b32_e32 v36, v0
	v_mov_b32_e32 v37, v0
	v_mov_b32_e32 v38, v0
	v_mov_b32_e32 v39, v0
	v_mov_b32_e32 v48, v0
	v_mov_b32_e32 v49, v0
	v_mov_b32_e32 v50, v0
	v_mov_b32_e32 v51, v0
	v_mov_b32_e32 v52, v0
	v_mov_b32_e32 v53, v0
	v_mov_b32_e32 v54, v0
	v_mov_b32_e32 v55, v0
	v_mov_b32_e32 v8, v0
	v_mov_b32_e32 v9, v0
	v_mov_b32_e32 v10, v0
	v_mov_b32_e32 v11, v0
	v_mov_b32_e32 v12, v0
	v_mov_b32_e32 v13, v0
	v_mov_b32_e32 v14, v0
	v_mov_b32_e32 v15, v0
	v_mov_b32_e32 v24, v0
	v_mov_b32_e32 v25, v0
	v_mov_b32_e32 v26, v0
	v_mov_b32_e32 v27, v0
	v_mov_b32_e32 v28, v0
	v_mov_b32_e32 v29, v0
	v_mov_b32_e32 v30, v0
	v_mov_b32_e32 v31, v0
	v_mov_b32_e32 v40, v0
	v_mov_b32_e32 v41, v0
	v_mov_b32_e32 v42, v0
	v_mov_b32_e32 v43, v0
	v_mov_b32_e32 v44, v0
	v_mov_b32_e32 v45, v0
	v_mov_b32_e32 v46, v0
	v_mov_b32_e32 v47, v0
	v_mov_b32_e32 v56, v0
	v_mov_b32_e32 v57, v0
	v_mov_b32_e32 v58, v0
	v_mov_b32_e32 v59, v0
	v_mov_b32_e32 v60, v0
	v_mov_b32_e32 v61, v0
	v_mov_b32_e32 v62, v0
	v_mov_b32_e32 v63, v0
	v_mov_b32_e32 v64, v0
	v_mov_b32_e32 v65, v0
	v_mov_b32_e32 v66, v0
	v_mov_b32_e32 v67, v0
	v_mov_b32_e32 v68, v0
	v_mov_b32_e32 v69, v0
	v_mov_b32_e32 v70, v0
	v_mov_b32_e32 v71, v0
	v_mov_b32_e32 v80, v0
	v_mov_b32_e32 v81, v0
	v_mov_b32_e32 v82, v0
	v_mov_b32_e32 v83, v0
	v_mov_b32_e32 v84, v0
	v_mov_b32_e32 v85, v0
	v_mov_b32_e32 v86, v0
	v_mov_b32_e32 v87, v0
	v_mov_b32_e32 v96, v0
	v_mov_b32_e32 v97, v0
	v_mov_b32_e32 v98, v0
	v_mov_b32_e32 v99, v0
	v_mov_b32_e32 v100, v0
	v_mov_b32_e32 v101, v0
	v_mov_b32_e32 v102, v0
	v_mov_b32_e32 v103, v0
	v_mov_b32_e32 v112, v0
	v_mov_b32_e32 v113, v0
	v_mov_b32_e32 v114, v0
	v_mov_b32_e32 v115, v0
	v_mov_b32_e32 v116, v0
	v_mov_b32_e32 v117, v0
	v_mov_b32_e32 v118, v0
	v_mov_b32_e32 v119, v0
	v_mov_b32_e32 v72, v0
	v_mov_b32_e32 v73, v0
	v_mov_b32_e32 v74, v0
	v_mov_b32_e32 v75, v0
	v_mov_b32_e32 v76, v0
	v_mov_b32_e32 v77, v0
	v_mov_b32_e32 v78, v0
	v_mov_b32_e32 v79, v0
	v_mov_b32_e32 v88, v0
	v_mov_b32_e32 v89, v0
	v_mov_b32_e32 v90, v0
	v_mov_b32_e32 v91, v0
	v_mov_b32_e32 v92, v0
	v_mov_b32_e32 v93, v0
	v_mov_b32_e32 v94, v0
	v_mov_b32_e32 v95, v0
	v_mov_b32_e32 v104, v0
	v_mov_b32_e32 v105, v0
	v_mov_b32_e32 v106, v0
	v_mov_b32_e32 v107, v0
	v_mov_b32_e32 v108, v0
	v_mov_b32_e32 v109, v0
	v_mov_b32_e32 v110, v0
	v_mov_b32_e32 v111, v0
	v_mov_b32_e32 v124, v0
	v_mov_b32_e32 v125, v0
	v_mov_b32_e32 v126, v0
	v_mov_b32_e32 v127, v0
	v_mov_b32_e32 v120, v0
	v_mov_b32_e32 v121, v0
	v_mov_b32_e32 v122, v0
	v_mov_b32_e32 v123, v0

; template <class Epi, class Sched, bool ALIGN_EPI = false, bool SP2 = false>
; __device__ __forceinline__ void gemm_phase(PG8_LAS unsigned char* lds, const Gemm g, const Sched& S, const Epi& E) {
;     ...
;         for (int t = 0; t < nt; t += 2) {
;             const bool last = (t == nt - 2);
;             const char* a1 = cA + (size_t)(t + 1) * kstep;
;     ...
; #pragma unroll
;         for (int a = 0; a < 2; ++a)
; #pragma unroll
;             for (int b = 0; b < 2; ++b)
; #pragma unroll
;                 for (int m = 0; m < 4; ++m)
; #pragma unroll
;                     for (int n = 0; n < 2; ++n) acc[a][b][m][n] = (f32x4){0.f, 0.f, 0.f, 0.f};
.LBB0_1220:
	s_andn2_b64 vcc, exec, s[24:25]
	s_waitcnt vmcnt(0)
	s_waitcnt lgkmcnt(0)
	s_cbranch_vccnz .LBB0_1223
	s_add_u32 s30, s30, 0x80
	s_addc_u32 s31, s31, 0
	s_add_u32 s63, s34, 0x100
	v_mov_b32_e32 v0, 0
	s_addc_u32 s64, s35, 0
	s_mov_b32 s34, 0
	v_mov_b32_e32 v1, v0
	v_mov_b32_e32 v2, v0
	v_mov_b32_e32 v3, v0
	v_mov_b32_e32 v4, v0
	v_mov_b32_e32 v5, v0
	v_mov_b32_e32 v6, v0
	v_mov_b32_e32 v7, v0
	v_mov_b32_e32 v16, v0
	v_mov_b32_e32 v17, v0
	v_mov_b32_e32 v18, v0
	v_mov_b32_e32 v19, v0
	v_mov_b32_e32 v20, v0
	v_mov_b32_e32 v21, v0
	v_mov_b32_e32 v22, v0
	v_mov_b32_e32 v23, v0
	v_mov_b32_e32 v32, v0
	v_mov_b32_e32 v33, v0
	v_mov_b32_e32 v34, v0
	v_mov_b32_e32 v35, v0
	v_mov_b32_e32 v36, v0
	v_mov_b32_e32 v37, v0
	v_mov_b32_e32 v38, v0
	v_mov_b32_e32 v39, v0
	v_mov_b32_e32 v48, v0
	v_mov_b32_e32 v49, v0
	v_mov_b32_e32 v50, v0
	v_mov_b32_e32 v51, v0
	v_mov_b32_e32 v52, v0
	v_mov_b32_e32 v53, v0
	v_mov_b32_e32 v54, v0
	v_mov_b32_e32 v55, v0
	v_mov_b32_e32 v8, v0
	v_mov_b32_e32 v9, v0
	v_mov_b32_e32 v10, v0
	v_mov_b32_e32 v11, v0
	v_mov_b32_e32 v12, v0
	v_mov_b32_e32 v13, v0
	v_mov_b32_e32 v14, v0
	v_mov_b32_e32 v15, v0
	v_mov_b32_e32 v24, v0
	v_mov_b32_e32 v25, v0
	v_mov_b32_e32 v26, v0
	v_mov_b32_e32 v27, v0
	v_mov_b32_e32 v28, v0
	v_mov_b32_e32 v29, v0
	v_mov_b32_e32 v30, v0
	v_mov_b32_e32 v31, v0
	v_mov_b32_e32 v40, v0
	v_mov_b32_e32 v41, v0
	v_mov_b32_e32 v42, v0
	v_mov_b32_e32 v43, v0
	v_mov_b32_e32 v44, v0
	v_mov_b32_e32 v45, v0
	v_mov_b32_e32 v46, v0
	v_mov_b32_e32 v47, v0
	v_mov_b32_e32 v56, v0
	v_mov_b32_e32 v57, v0
	v_mov_b32_e32 v58, v0
	v_mov_b32_e32 v59, v0
	v_mov_b32_e32 v60, v0
	v_mov_b32_e32 v61, v0
	v_mov_b32_e32 v62, v0
	v_mov_b32_e32 v63, v0
	v_mov_b32_e32 v64, v0
	v_mov_b32_e32 v65, v0
	v_mov_b32_e32 v66, v0
	v_mov_b32_e32 v67, v0
	v_mov_b32_e32 v68, v0
	v_mov_b32_e32 v69, v0
	v_mov_b32_e32 v70, v0
	v_mov_b32_e32 v71, v0
	v_mov_b32_e32 v80, v0
	v_mov_b32_e32 v81, v0
	v_mov_b32_e32 v82, v0
	v_mov_b32_e32 v83, v0
	v_mov_b32_e32 v84, v0
	v_mov_b32_e32 v85, v0
	v_mov_b32_e32 v86, v0
	v_mov_b32_e32 v87, v0
	v_mov_b32_e32 v96, v0
	v_mov_b32_e32 v97, v0
	v_mov_b32_e32 v98, v0
	v_mov_b32_e32 v99, v0
	v_mov_b32_e32 v100, v0
	v_mov_b32_e32 v101, v0
	v_mov_b32_e32 v102, v0
	v_mov_b32_e32 v103, v0
	v_mov_b32_e32 v112, v0
	v_mov_b32_e32 v113, v0
	v_mov_b32_e32 v114, v0
	v_mov_b32_e32 v115, v0
	v_mov_b32_e32 v116, v0
	v_mov_b32_e32 v117, v0
	v_mov_b32_e32 v118, v0
	v_mov_b32_e32 v119, v0
	v_mov_b32_e32 v72, v0
	v_mov_b32_e32 v73, v0
	v_mov_b32_e32 v74, v0
	v_mov_b32_e32 v75, v0
	v_mov_b32_e32 v76, v0
	v_mov_b32_e32 v77, v0
	v_mov_b32_e32 v78, v0
	v_mov_b32_e32 v79, v0
	v_mov_b32_e32 v88, v0
	v_mov_b32_e32 v89, v0
	v_mov_b32_e32 v90, v0
	v_mov_b32_e32 v91, v0
	v_mov_b32_e32 v92, v0
	v_mov_b32_e32 v93, v0
	v_mov_b32_e32 v94, v0
	v_mov_b32_e32 v95, v0
	v_mov_b32_e32 v104, v0
	v_mov_b32_e32 v105, v0
	v_mov_b32_e32 v106, v0
	v_mov_b32_e32 v107, v0
	v_mov_b32_e32 v108, v0
	v_mov_b32_e32 v109, v0
	v_mov_b32_e32 v110, v0
	v_mov_b32_e32 v111, v0
	v_mov_b32_e32 v120, v0
	v_mov_b32_e32 v121, v0
	v_mov_b32_e32 v122, v0
	v_mov_b32_e32 v123, v0
	v_mov_b32_e32 v124, v0
	v_mov_b32_e32 v125, v0
	v_mov_b32_e32 v126, v0
	v_mov_b32_e32 v127, v0

; template <class Epi, class Sched, bool ALIGN_EPI = false, bool SP2 = false>
; __device__ __forceinline__ void gemm_phase(PG8_LAS unsigned char* lds, const Gemm g, const Sched& S, const Epi& E) {
;     ...
;         for (int t = 0; t < nt; t += 2) {
;             const bool last = (t == nt - 2);
;             const char* a1 = cA + (size_t)(t + 1) * kstep;
;     ...
; #pragma unroll
;         for (int a = 0; a < 2; ++a)
; #pragma unroll
;             for (int b = 0; b < 2; ++b)
; #pragma unroll
;                 for (int m = 0; m < 4; ++m)
; #pragma unroll
;                     for (int n = 0; n < 2; ++n) acc[a][b][m][n] = (f32x4){0.f, 0.f, 0.f, 0.f};
.LBB0_1315:
	s_andn2_b64 vcc, exec, s[20:21]
	s_waitcnt vmcnt(0)
	s_cbranch_vccnz .LBB0_1318
	s_add_u32 s26, s26, 0x80
	s_addc_u32 s27, s27, 0
	s_add_u32 s62, s28, 0x100
	v_mov_b32_e32 v8, 0
	s_addc_u32 s63, s29, 0
	s_mov_b32 s28, 0
	v_mov_b32_e32 v9, v8
	v_mov_b32_e32 v10, v8
	v_mov_b32_e32 v11, v8
	v_mov_b32_e32 v12, v8
	v_mov_b32_e32 v13, v8
	v_mov_b32_e32 v14, v8
	v_mov_b32_e32 v15, v8
	v_mov_b32_e32 v24, v8
	v_mov_b32_e32 v25, v8
	v_mov_b32_e32 v26, v8
	v_mov_b32_e32 v27, v8
	v_mov_b32_e32 v28, v8
	v_mov_b32_e32 v29, v8
	v_mov_b32_e32 v30, v8
	v_mov_b32_e32 v31, v8
	v_mov_b32_e32 v40, v8
	v_mov_b32_e32 v41, v8
	v_mov_b32_e32 v42, v8
	v_mov_b32_e32 v43, v8
	v_mov_b32_e32 v44, v8
	v_mov_b32_e32 v45, v8
	v_mov_b32_e32 v46, v8
	v_mov_b32_e32 v47, v8
	v_mov_b32_e32 v56, v8
	v_mov_b32_e32 v57, v8
	v_mov_b32_e32 v58, v8
	v_mov_b32_e32 v59, v8
	v_mov_b32_e32 v60, v8
	v_mov_b32_e32 v61, v8
	v_mov_b32_e32 v62, v8
	v_mov_b32_e32 v63, v8
	v_mov_b32_e32 v0, v8
	v_mov_b32_e32 v1, v8
	v_mov_b32_e32 v2, v8
	v_mov_b32_e32 v3, v8
	v_mov_b32_e32 v4, v8
	v_mov_b32_e32 v5, v8
	v_mov_b32_e32 v6, v8
	v_mov_b32_e32 v7, v8
	v_mov_b32_e32 v16, v8
	v_mov_b32_e32 v17, v8
	v_mov_b32_e32 v18, v8
	v_mov_b32_e32 v19, v8
	v_mov_b32_e32 v20, v8
	v_mov_b32_e32 v21, v8
	v_mov_b32_e32 v22, v8
	v_mov_b32_e32 v23, v8
	v_mov_b32_e32 v32, v8
	v_mov_b32_e32 v33, v8
	v_mov_b32_e32 v34, v8
	v_mov_b32_e32 v35, v8
	v_mov_b32_e32 v36, v8
	v_mov_b32_e32 v37, v8
	v_mov_b32_e32 v38, v8
	v_mov_b32_e32 v39, v8
	v_mov_b32_e32 v48, v8
	v_mov_b32_e32 v49, v8
	v_mov_b32_e32 v50, v8
	v_mov_b32_e32 v51, v8
	v_mov_b32_e32 v52, v8
	v_mov_b32_e32 v53, v8
	v_mov_b32_e32 v54, v8
	v_mov_b32_e32 v55, v8
	v_mov_b32_e32 v72, v8
	v_mov_b32_e32 v73, v8
	v_mov_b32_e32 v74, v8
	v_mov_b32_e32 v75, v8
	v_mov_b32_e32 v76, v8
	v_mov_b32_e32 v77, v8
	v_mov_b32_e32 v78, v8
	v_mov_b32_e32 v79, v8
	v_mov_b32_e32 v88, v8
	v_mov_b32_e32 v89, v8
	v_mov_b32_e32 v90, v8
	v_mov_b32_e32 v91, v8
	v_mov_b32_e32 v92, v8
	v_mov_b32_e32 v93, v8
	v_mov_b32_e32 v94, v8
	v_mov_b32_e32 v95, v8
	v_mov_b32_e32 v104, v8
	v_mov_b32_e32 v105, v8
	v_mov_b32_e32 v106, v8
	v_mov_b32_e32 v107, v8
	v_mov_b32_e32 v108, v8
	v_mov_b32_e32 v109, v8
	v_mov_b32_e32 v110, v8
	v_mov_b32_e32 v111, v8
	v_mov_b32_e32 v120, v8
	v_mov_b32_e32 v121, v8
	v_mov_b32_e32 v122, v8
	v_mov_b32_e32 v123, v8
	v_mov_b32_e32 v124, v8
	v_mov_b32_e32 v125, v8
	v_mov_b32_e32 v126, v8
	v_mov_b32_e32 v127, v8
	v_mov_b32_e32 v64, v8
	v_mov_b32_e32 v65, v8
	v_mov_b32_e32 v66, v8
	v_mov_b32_e32 v67, v8
	v_mov_b32_e32 v68, v8
	v_mov_b32_e32 v69, v8
	v_mov_b32_e32 v70, v8
	v_mov_b32_e32 v71, v8
	v_mov_b32_e32 v80, v8
	v_mov_b32_e32 v81, v8
	v_mov_b32_e32 v82, v8
	v_mov_b32_e32 v83, v8
	v_mov_b32_e32 v84, v8
	v_mov_b32_e32 v85, v8
	v_mov_b32_e32 v86, v8
	v_mov_b32_e32 v87, v8
	v_mov_b32_e32 v96, v8
	v_mov_b32_e32 v97, v8
	v_mov_b32_e32 v98, v8
	v_mov_b32_e32 v99, v8
	v_mov_b32_e32 v100, v8
	v_mov_b32_e32 v101, v8
	v_mov_b32_e32 v102, v8
	v_mov_b32_e32 v103, v8
	v_mov_b32_e32 v112, v8
	v_mov_b32_e32 v113, v8
	v_mov_b32_e32 v114, v8
	v_mov_b32_e32 v115, v8
	v_mov_b32_e32 v116, v8
	v_mov_b32_e32 v117, v8
	v_mov_b32_e32 v118, v8
	v_mov_b32_e32 v119, v8

; template <class Epi, class Sched, bool ALIGN_EPI = false, bool SP2 = false>
; __device__ __forceinline__ void gemm_phase(PG8_LAS unsigned char* lds, const Gemm g, const Sched& S, const Epi& E) {
;     ...
;         for (int t = 0; t < nt; t += 2) {
;             const bool last = (t == nt - 2);
;             const char* a1 = cA + (size_t)(t + 1) * kstep;
;     ...
; #pragma unroll
;         for (int a = 0; a < 2; ++a)
; #pragma unroll
;             for (int b = 0; b < 2; ++b)
; #pragma unroll
;                 for (int m = 0; m < 4; ++m)
; #pragma unroll
;                     for (int n = 0; n < 2; ++n) acc[a][b][m][n] = (f32x4){0.f, 0.f, 0.f, 0.f};
.LBB0_1409:
	v_mov_b32_e32 v151, 0
	s_andn2_b64 vcc, exec, s[24:25]
	v_mov_b32_e32 v150, 0
	v_mov_b32_e32 v155, 0
	v_mov_b32_e32 v154, 0
	v_mov_b32_e32 v153, 0
	v_mov_b32_e32 v152, 0
	v_mov_b32_e32 v149, 0
	v_mov_b32_e32 v148, 0
	s_waitcnt vmcnt(0)
	v_mov_b32_e32 v145, 0
	v_mov_b32_e32 v144, 0
	v_mov_b32_e32 v147, 0
	v_mov_b32_e32 v146, 0
	s_waitcnt lgkmcnt(0)
	s_cbranch_vccnz .LBB0_1413
	s_add_u32 s30, s30, 0x80
	s_addc_u32 s31, s31, 0
	s_add_u32 s63, s34, 0x100
	v_mov_b32_e32 v0, 0
	s_addc_u32 s64, s35, 0
	s_mov_b32 s34, 0
	v_mov_b32_e32 v1, v0
	v_mov_b32_e32 v2, v0
	v_mov_b32_e32 v3, v0
	v_mov_b32_e32 v4, v0
	v_mov_b32_e32 v5, v0
	v_mov_b32_e32 v6, v0
	v_mov_b32_e32 v7, v0
	v_mov_b32_e32 v8, v0
	v_mov_b32_e32 v9, v0
	v_mov_b32_e32 v10, v0
	v_mov_b32_e32 v11, v0
	v_mov_b32_e32 v12, v0
	v_mov_b32_e32 v13, v0
	v_mov_b32_e32 v14, v0
	v_mov_b32_e32 v15, v0
	v_mov_b32_e32 v20, v0
	v_mov_b32_e32 v21, v0
	v_mov_b32_e32 v22, v0
	v_mov_b32_e32 v23, v0
	v_mov_b32_e32 v28, v0
	v_mov_b32_e32 v29, v0
	v_mov_b32_e32 v30, v0
	v_mov_b32_e32 v31, v0
	v_mov_b32_e32 v36, v0
	v_mov_b32_e32 v37, v0
	v_mov_b32_e32 v38, v0
	v_mov_b32_e32 v39, v0
	v_mov_b32_e32 v44, v0
	v_mov_b32_e32 v45, v0
	v_mov_b32_e32 v46, v0
	v_mov_b32_e32 v47, v0
	v_mov_b32_e32 v16, v0
	v_mov_b32_e32 v17, v0
	v_mov_b32_e32 v18, v0
	v_mov_b32_e32 v19, v0
	v_mov_b32_e32 v24, v0
	v_mov_b32_e32 v25, v0
	v_mov_b32_e32 v26, v0
	v_mov_b32_e32 v27, v0
	v_mov_b32_e32 v32, v0
	v_mov_b32_e32 v33, v0
	v_mov_b32_e32 v34, v0
	v_mov_b32_e32 v35, v0
	v_mov_b32_e32 v40, v0
	v_mov_b32_e32 v41, v0
	v_mov_b32_e32 v42, v0
	v_mov_b32_e32 v43, v0
	v_mov_b32_e32 v48, v0
	v_mov_b32_e32 v49, v0
	v_mov_b32_e32 v50, v0
	v_mov_b32_e32 v51, v0
	v_mov_b32_e32 v52, v0
	v_mov_b32_e32 v53, v0
	v_mov_b32_e32 v54, v0
	v_mov_b32_e32 v55, v0
	v_mov_b32_e32 v56, v0
	v_mov_b32_e32 v57, v0
	v_mov_b32_e32 v58, v0
	v_mov_b32_e32 v59, v0
	v_mov_b32_e32 v60, v0
	v_mov_b32_e32 v61, v0
	v_mov_b32_e32 v62, v0
	v_mov_b32_e32 v63, v0
	v_mov_b32_e32 v64, v0
	v_mov_b32_e32 v65, v0
	v_mov_b32_e32 v66, v0
	v_mov_b32_e32 v67, v0
	v_mov_b32_e32 v68, v0
	v_mov_b32_e32 v69, v0
	v_mov_b32_e32 v70, v0
	v_mov_b32_e32 v71, v0
	v_mov_b32_e32 v72, v0
	v_mov_b32_e32 v73, v0
	v_mov_b32_e32 v74, v0
	v_mov_b32_e32 v75, v0
	v_mov_b32_e32 v76, v0
	v_mov_b32_e32 v77, v0
	v_mov_b32_e32 v78, v0
	v_mov_b32_e32 v79, v0
	v_mov_b32_e32 v84, v0
	v_mov_b32_e32 v85, v0
	v_mov_b32_e32 v86, v0
	v_mov_b32_e32 v87, v0
	v_mov_b32_e32 v92, v0
	v_mov_b32_e32 v93, v0
	v_mov_b32_e32 v94, v0
	v_mov_b32_e32 v95, v0
	v_mov_b32_e32 v100, v0
	v_mov_b32_e32 v101, v0
	v_mov_b32_e32 v102, v0
	v_mov_b32_e32 v103, v0
	v_mov_b32_e32 v108, v0
	v_mov_b32_e32 v109, v0
	v_mov_b32_e32 v110, v0
	v_mov_b32_e32 v111, v0
	v_mov_b32_e32 v80, v0
	v_mov_b32_e32 v81, v0
	v_mov_b32_e32 v82, v0
	v_mov_b32_e32 v83, v0
	v_mov_b32_e32 v88, v0
	v_mov_b32_e32 v89, v0
	v_mov_b32_e32 v90, v0
	v_mov_b32_e32 v91, v0
	v_mov_b32_e32 v96, v0
	v_mov_b32_e32 v97, v0
	v_mov_b32_e32 v98, v0
	v_mov_b32_e32 v99, v0
	v_mov_b32_e32 v104, v0
	v_mov_b32_e32 v105, v0
	v_mov_b32_e32 v106, v0
	v_mov_b32_e32 v107, v0
	v_mov_b32_e32 v112, v0
	v_mov_b32_e32 v113, v0
	v_mov_b32_e32 v114, v0
	v_mov_b32_e32 v115, v0
	v_mov_b32_e32 v116, v0
	v_mov_b32_e32 v117, v0
	v_mov_b32_e32 v118, v0
	v_mov_b32_e32 v119, v0
	v_mov_b32_e32 v120, v0
	v_mov_b32_e32 v121, v0
	v_mov_b32_e32 v122, v0
	v_mov_b32_e32 v123, v0
	v_mov_b32_e32 v124, v0
	v_mov_b32_e32 v125, v0
	v_mov_b32_e32 v126, v0
	v_mov_b32_e32 v127, v0

; template <class Epi, class Sched, bool ALIGN_EPI = false, bool SP2 = false>
; __device__ __forceinline__ void gemm_phase(PG8_LAS unsigned char* lds, const Gemm g, const Sched& S, const Epi& E) {
;     ...
;         for (int t = 0; t < nt; t += 2) {
;             const bool last = (t == nt - 2);
;             const char* a1 = cA + (size_t)(t + 1) * kstep;
;     ...
; #pragma unroll
;         for (int a = 0; a < 2; ++a)
; #pragma unroll
;             for (int b = 0; b < 2; ++b)
; #pragma unroll
;                 for (int m = 0; m < 4; ++m)
; #pragma unroll
;                     for (int n = 0; n < 2; ++n) acc[a][b][m][n] = (f32x4){0.f, 0.f, 0.f, 0.f};
.LBB0_1729:
	s_andn2_b64 vcc, exec, s[36:37]
	s_waitcnt vmcnt(0)
	s_waitcnt lgkmcnt(0)
	s_waitcnt lgkmcnt(0)
	s_cbranch_vccnz .LBB0_1732
	s_add_u32 s0, s8, 0x80
	s_addc_u32 s1, s9, 0
	s_add_u32 s8, s6, 0x100
	v_mov_b32_e32 v0, 0
	s_addc_u32 s9, s7, 0
	s_mov_b32 s6, 0
	v_mov_b32_e32 v1, v0
	v_mov_b32_e32 v2, v0
	v_mov_b32_e32 v3, v0
	v_mov_b32_e32 v4, v0
	v_mov_b32_e32 v5, v0
	v_mov_b32_e32 v6, v0
	v_mov_b32_e32 v7, v0
	v_mov_b32_e32 v16, v0
	v_mov_b32_e32 v17, v0
	v_mov_b32_e32 v18, v0
	v_mov_b32_e32 v19, v0
	v_mov_b32_e32 v20, v0
	v_mov_b32_e32 v21, v0
	v_mov_b32_e32 v22, v0
	v_mov_b32_e32 v23, v0
	v_mov_b32_e32 v32, v0
	v_mov_b32_e32 v33, v0
	v_mov_b32_e32 v34, v0
	v_mov_b32_e32 v35, v0
	v_mov_b32_e32 v36, v0
	v_mov_b32_e32 v37, v0
	v_mov_b32_e32 v38, v0
	v_mov_b32_e32 v39, v0
	v_mov_b32_e32 v48, v0
	v_mov_b32_e32 v49, v0
	v_mov_b32_e32 v50, v0
	v_mov_b32_e32 v51, v0
	v_mov_b32_e32 v52, v0
	v_mov_b32_e32 v53, v0
	v_mov_b32_e32 v54, v0
	v_mov_b32_e32 v55, v0
	v_mov_b32_e32 v8, v0
	v_mov_b32_e32 v9, v0
	v_mov_b32_e32 v10, v0
	v_mov_b32_e32 v11, v0
	v_mov_b32_e32 v12, v0
	v_mov_b32_e32 v13, v0
	v_mov_b32_e32 v14, v0
	v_mov_b32_e32 v15, v0
	v_mov_b32_e32 v24, v0
	v_mov_b32_e32 v25, v0
	v_mov_b32_e32 v26, v0
	v_mov_b32_e32 v27, v0
	v_mov_b32_e32 v28, v0
	v_mov_b32_e32 v29, v0
	v_mov_b32_e32 v30, v0
	v_mov_b32_e32 v31, v0
	v_mov_b32_e32 v40, v0
	v_mov_b32_e32 v41, v0
	v_mov_b32_e32 v42, v0
	v_mov_b32_e32 v43, v0
	v_mov_b32_e32 v44, v0
	v_mov_b32_e32 v45, v0
	v_mov_b32_e32 v46, v0
	v_mov_b32_e32 v47, v0
	v_mov_b32_e32 v56, v0
	v_mov_b32_e32 v57, v0
	v_mov_b32_e32 v58, v0
	v_mov_b32_e32 v59, v0
	v_mov_b32_e32 v60, v0
	v_mov_b32_e32 v61, v0
	v_mov_b32_e32 v62, v0
	v_mov_b32_e32 v63, v0
	v_mov_b32_e32 v64, v0
	v_mov_b32_e32 v65, v0
	v_mov_b32_e32 v66, v0
	v_mov_b32_e32 v67, v0
	v_mov_b32_e32 v68, v0
	v_mov_b32_e32 v69, v0
	v_mov_b32_e32 v70, v0
	v_mov_b32_e32 v71, v0
	v_mov_b32_e32 v80, v0
	v_mov_b32_e32 v81, v0
	v_mov_b32_e32 v82, v0
	v_mov_b32_e32 v83, v0
	v_mov_b32_e32 v84, v0
	v_mov_b32_e32 v85, v0
	v_mov_b32_e32 v86, v0
	v_mov_b32_e32 v87, v0
	v_mov_b32_e32 v96, v0
	v_mov_b32_e32 v97, v0
	v_mov_b32_e32 v98, v0
	v_mov_b32_e32 v99, v0
	v_mov_b32_e32 v100, v0
	v_mov_b32_e32 v101, v0
	v_mov_b32_e32 v102, v0
	v_mov_b32_e32 v103, v0
	v_mov_b32_e32 v112, v0
	v_mov_b32_e32 v113, v0
	v_mov_b32_e32 v114, v0
	v_mov_b32_e32 v115, v0
	v_mov_b32_e32 v116, v0
	v_mov_b32_e32 v117, v0
	v_mov_b32_e32 v118, v0
	v_mov_b32_e32 v119, v0
	v_mov_b32_e32 v72, v0
	v_mov_b32_e32 v73, v0
	v_mov_b32_e32 v74, v0
	v_mov_b32_e32 v75, v0
	v_mov_b32_e32 v76, v0
	v_mov_b32_e32 v77, v0
	v_mov_b32_e32 v78, v0
	v_mov_b32_e32 v79, v0
	v_mov_b32_e32 v88, v0
	v_mov_b32_e32 v89, v0
	v_mov_b32_e32 v90, v0
	v_mov_b32_e32 v91, v0
	v_mov_b32_e32 v92, v0
	v_mov_b32_e32 v93, v0
	v_mov_b32_e32 v94, v0
	v_mov_b32_e32 v95, v0
	v_mov_b32_e32 v104, v0
	v_mov_b32_e32 v105, v0
	v_mov_b32_e32 v106, v0
	v_mov_b32_e32 v107, v0
	v_mov_b32_e32 v108, v0
	v_mov_b32_e32 v109, v0
	v_mov_b32_e32 v110, v0
	v_mov_b32_e32 v111, v0
	v_mov_b32_e32 v120, v0
	v_mov_b32_e32 v121, v0
	v_mov_b32_e32 v122, v0
	v_mov_b32_e32 v123, v0
	v_mov_b32_e32 v124, v0
	v_mov_b32_e32 v125, v0
	v_mov_b32_e32 v126, v0
	v_mov_b32_e32 v127, v0

; template <class Epi, class Sched, bool ALIGN_EPI = false, bool SP2 = false>
; __device__ __forceinline__ void gemm_phase(PG8_LAS unsigned char* lds, const Gemm g, const Sched& S, const Epi& E) {
;     ...
;         for (int t = 0; t < nt; t += 2) {
;             const bool last = (t == nt - 2);
;             const char* a1 = cA + (size_t)(t + 1) * kstep;
;     ...
; #pragma unroll
;         for (int a = 0; a < 2; ++a)
; #pragma unroll
;             for (int b = 0; b < 2; ++b)
; #pragma unroll
;                 for (int m = 0; m < 4; ++m)
; #pragma unroll
;                     for (int n = 0; n < 2; ++n) acc[a][b][m][n] = (f32x4){0.f, 0.f, 0.f, 0.f};
.LBB0_2050:
	s_andn2_b64 vcc, exec, s[24:25]
	s_waitcnt vmcnt(0)
	s_cbranch_vccnz .LBB0_2053
	s_add_u32 s0, s6, 0x80
	s_addc_u32 s1, s7, 0
	s_add_u32 s6, s4, 0x100
	v_mov_b32_e32 v0, 0
	s_addc_u32 s7, s5, 0
	s_mov_b32 s4, 0
	v_mov_b32_e32 v1, v0
	v_mov_b32_e32 v2, v0
	v_mov_b32_e32 v3, v0
	v_mov_b32_e32 v4, v0
	v_mov_b32_e32 v5, v0
	v_mov_b32_e32 v6, v0
	v_mov_b32_e32 v7, v0
	v_mov_b32_e32 v16, v0
	v_mov_b32_e32 v17, v0
	v_mov_b32_e32 v18, v0
	v_mov_b32_e32 v19, v0
	v_mov_b32_e32 v20, v0
	v_mov_b32_e32 v21, v0
	v_mov_b32_e32 v22, v0
	v_mov_b32_e32 v23, v0
	v_mov_b32_e32 v32, v0
	v_mov_b32_e32 v33, v0
	v_mov_b32_e32 v34, v0
	v_mov_b32_e32 v35, v0
	v_mov_b32_e32 v36, v0
	v_mov_b32_e32 v37, v0
	v_mov_b32_e32 v38, v0
	v_mov_b32_e32 v39, v0
	v_mov_b32_e32 v48, v0
	v_mov_b32_e32 v49, v0
	v_mov_b32_e32 v50, v0
	v_mov_b32_e32 v51, v0
	v_mov_b32_e32 v52, v0
	v_mov_b32_e32 v53, v0
	v_mov_b32_e32 v54, v0
	v_mov_b32_e32 v55, v0
	v_mov_b32_e32 v8, v0
	v_mov_b32_e32 v9, v0
	v_mov_b32_e32 v10, v0
	v_mov_b32_e32 v11, v0
	v_mov_b32_e32 v12, v0
	v_mov_b32_e32 v13, v0
	v_mov_b32_e32 v14, v0
	v_mov_b32_e32 v15, v0
	v_mov_b32_e32 v24, v0
	v_mov_b32_e32 v25, v0
	v_mov_b32_e32 v26, v0
	v_mov_b32_e32 v27, v0
	v_mov_b32_e32 v28, v0
	v_mov_b32_e32 v29, v0
	v_mov_b32_e32 v30, v0
	v_mov_b32_e32 v31, v0
	v_mov_b32_e32 v40, v0
	v_mov_b32_e32 v41, v0
	v_mov_b32_e32 v42, v0
	v_mov_b32_e32 v43, v0
	v_mov_b32_e32 v44, v0
	v_mov_b32_e32 v45, v0
	v_mov_b32_e32 v46, v0
	v_mov_b32_e32 v47, v0
	v_mov_b32_e32 v56, v0
	v_mov_b32_e32 v57, v0
	v_mov_b32_e32 v58, v0
	v_mov_b32_e32 v59, v0
	v_mov_b32_e32 v60, v0
	v_mov_b32_e32 v61, v0
	v_mov_b32_e32 v62, v0
	v_mov_b32_e32 v63, v0
	v_mov_b32_e32 v64, v0
	v_mov_b32_e32 v65, v0
	v_mov_b32_e32 v66, v0
	v_mov_b32_e32 v67, v0
	v_mov_b32_e32 v68, v0
	v_mov_b32_e32 v69, v0
	v_mov_b32_e32 v70, v0
	v_mov_b32_e32 v71, v0
	v_mov_b32_e32 v80, v0
	v_mov_b32_e32 v81, v0
	v_mov_b32_e32 v82, v0
	v_mov_b32_e32 v83, v0
	v_mov_b32_e32 v84, v0
	v_mov_b32_e32 v85, v0
	v_mov_b32_e32 v86, v0
	v_mov_b32_e32 v87, v0
	v_mov_b32_e32 v96, v0
	v_mov_b32_e32 v97, v0
	v_mov_b32_e32 v98, v0
	v_mov_b32_e32 v99, v0
	v_mov_b32_e32 v100, v0
	v_mov_b32_e32 v101, v0
	v_mov_b32_e32 v102, v0
	v_mov_b32_e32 v103, v0
	v_mov_b32_e32 v112, v0
	v_mov_b32_e32 v113, v0
	v_mov_b32_e32 v114, v0
	v_mov_b32_e32 v115, v0
	v_mov_b32_e32 v116, v0
	v_mov_b32_e32 v117, v0
	v_mov_b32_e32 v118, v0
	v_mov_b32_e32 v119, v0
	v_mov_b32_e32 v72, v0
	v_mov_b32_e32 v73, v0
	v_mov_b32_e32 v74, v0
	v_mov_b32_e32 v75, v0
	v_mov_b32_e32 v76, v0
	v_mov_b32_e32 v77, v0
	v_mov_b32_e32 v78, v0
	v_mov_b32_e32 v79, v0
	v_mov_b32_e32 v88, v0
	v_mov_b32_e32 v89, v0
	v_mov_b32_e32 v90, v0
	v_mov_b32_e32 v91, v0
	v_mov_b32_e32 v92, v0
	v_mov_b32_e32 v93, v0
	v_mov_b32_e32 v94, v0
	v_mov_b32_e32 v95, v0
	v_mov_b32_e32 v104, v0
	v_mov_b32_e32 v105, v0
	v_mov_b32_e32 v106, v0
	v_mov_b32_e32 v107, v0
	v_mov_b32_e32 v108, v0
	v_mov_b32_e32 v109, v0
	v_mov_b32_e32 v110, v0
	v_mov_b32_e32 v111, v0
	v_mov_b32_e32 v124, v0
	v_mov_b32_e32 v125, v0
	v_mov_b32_e32 v126, v0
	v_mov_b32_e32 v127, v0
	v_mov_b32_e32 v120, v0
	v_mov_b32_e32 v121, v0
	v_mov_b32_e32 v122, v0
	v_mov_b32_e32 v123, v0

; template <class Epi, class Sched, bool ALIGN_EPI = false, bool SP2 = false>
; __device__ __forceinline__ void gemm_phase(PG8_LAS unsigned char* lds, const Gemm g, const Sched& S, const Epi& E) {
;     ...
;         for (int t = 0; t < nt; t += 2) {
;             const bool last = (t == nt - 2);
;             const char* a1 = cA + (size_t)(t + 1) * kstep;
;     ...
; #pragma unroll
;         for (int a = 0; a < 2; ++a)
; #pragma unroll
;             for (int b = 0; b < 2; ++b)
; #pragma unroll
;                 for (int m = 0; m < 4; ++m)
; #pragma unroll
;                     for (int n = 0; n < 2; ++n) acc[a][b][m][n] = (f32x4){0.f, 0.f, 0.f, 0.f};
.LBB0_2163:
	s_andn2_b64 vcc, exec, s[22:23]
	s_cbranch_vccnz .LBB0_2166
	s_add_u32 s30, s30, 0x80
	s_addc_u32 s31, s31, 0
	s_add_u32 s77, s34, 0x100
	v_mov_b32_e32 v0, 0
	s_addc_u32 s78, s35, 0
	s_mov_b32 s34, 0
	v_mov_b32_e32 v1, v0
	v_mov_b32_e32 v2, v0
	v_mov_b32_e32 v3, v0
	v_mov_b32_e32 v4, v0
	v_mov_b32_e32 v5, v0
	v_mov_b32_e32 v6, v0
	v_mov_b32_e32 v7, v0
	v_mov_b32_e32 v16, v0
	v_mov_b32_e32 v17, v0
	v_mov_b32_e32 v18, v0
	v_mov_b32_e32 v19, v0
	v_mov_b32_e32 v20, v0
	v_mov_b32_e32 v21, v0
	v_mov_b32_e32 v22, v0
	v_mov_b32_e32 v23, v0
	v_mov_b32_e32 v32, v0
	v_mov_b32_e32 v33, v0
	v_mov_b32_e32 v34, v0
	v_mov_b32_e32 v35, v0
	v_mov_b32_e32 v36, v0
	v_mov_b32_e32 v37, v0
	v_mov_b32_e32 v38, v0
	v_mov_b32_e32 v39, v0
	v_mov_b32_e32 v48, v0
	v_mov_b32_e32 v49, v0
	v_mov_b32_e32 v50, v0
	v_mov_b32_e32 v51, v0
	v_mov_b32_e32 v52, v0
	v_mov_b32_e32 v53, v0
	v_mov_b32_e32 v54, v0
	v_mov_b32_e32 v55, v0
	v_mov_b32_e32 v8, v0
	v_mov_b32_e32 v9, v0
	v_mov_b32_e32 v10, v0
	v_mov_b32_e32 v11, v0
	v_mov_b32_e32 v12, v0
	v_mov_b32_e32 v13, v0
	v_mov_b32_e32 v14, v0
	v_mov_b32_e32 v15, v0
	v_mov_b32_e32 v24, v0
	v_mov_b32_e32 v25, v0
	v_mov_b32_e32 v26, v0
	v_mov_b32_e32 v27, v0
	v_mov_b32_e32 v28, v0
	v_mov_b32_e32 v29, v0
	v_mov_b32_e32 v30, v0
	v_mov_b32_e32 v31, v0
	v_mov_b32_e32 v40, v0
	v_mov_b32_e32 v41, v0
	v_mov_b32_e32 v42, v0
	v_mov_b32_e32 v43, v0
	v_mov_b32_e32 v44, v0
	v_mov_b32_e32 v45, v0
	v_mov_b32_e32 v46, v0
	v_mov_b32_e32 v47, v0
	v_mov_b32_e32 v56, v0
	v_mov_b32_e32 v57, v0
	v_mov_b32_e32 v58, v0
	v_mov_b32_e32 v59, v0
	v_mov_b32_e32 v60, v0
	v_mov_b32_e32 v61, v0
	v_mov_b32_e32 v62, v0
	v_mov_b32_e32 v63, v0
	v_mov_b32_e32 v64, v0
	v_mov_b32_e32 v65, v0
	v_mov_b32_e32 v66, v0
	v_mov_b32_e32 v67, v0
	v_mov_b32_e32 v68, v0
	v_mov_b32_e32 v69, v0
	v_mov_b32_e32 v70, v0
	v_mov_b32_e32 v71, v0
	v_mov_b32_e32 v80, v0
	v_mov_b32_e32 v81, v0
	v_mov_b32_e32 v82, v0
	v_mov_b32_e32 v83, v0
	v_mov_b32_e32 v84, v0
	v_mov_b32_e32 v85, v0
	v_mov_b32_e32 v86, v0
	v_mov_b32_e32 v87, v0
	v_mov_b32_e32 v96, v0
	v_mov_b32_e32 v97, v0
	v_mov_b32_e32 v98, v0
	v_mov_b32_e32 v99, v0
	v_mov_b32_e32 v100, v0
	v_mov_b32_e32 v101, v0
	v_mov_b32_e32 v102, v0
	v_mov_b32_e32 v103, v0
	v_mov_b32_e32 v112, v0
	v_mov_b32_e32 v113, v0
	v_mov_b32_e32 v114, v0
	v_mov_b32_e32 v115, v0
	v_mov_b32_e32 v116, v0
	v_mov_b32_e32 v117, v0
	v_mov_b32_e32 v118, v0
	v_mov_b32_e32 v119, v0
	v_mov_b32_e32 v72, v0
	v_mov_b32_e32 v73, v0
	v_mov_b32_e32 v74, v0
	v_mov_b32_e32 v75, v0
	v_mov_b32_e32 v76, v0
	v_mov_b32_e32 v77, v0
	v_mov_b32_e32 v78, v0
	v_mov_b32_e32 v79, v0
	v_mov_b32_e32 v88, v0
	v_mov_b32_e32 v89, v0
	v_mov_b32_e32 v90, v0
	v_mov_b32_e32 v91, v0
	v_mov_b32_e32 v92, v0
	v_mov_b32_e32 v93, v0
	v_mov_b32_e32 v94, v0
	v_mov_b32_e32 v95, v0
	v_mov_b32_e32 v104, v0
	v_mov_b32_e32 v105, v0
	v_mov_b32_e32 v106, v0
	v_mov_b32_e32 v107, v0
	v_mov_b32_e32 v108, v0
	v_mov_b32_e32 v109, v0
	v_mov_b32_e32 v110, v0
	v_mov_b32_e32 v111, v0
	v_mov_b32_e32 v124, v0
	v_mov_b32_e32 v125, v0
	v_mov_b32_e32 v126, v0
	v_mov_b32_e32 v127, v0
	v_mov_b32_e32 v120, v0
	v_mov_b32_e32 v121, v0
	v_mov_b32_e32 v122, v0
	v_mov_b32_e32 v123, v0

; template <class Epi, class Sched, bool ALIGN_EPI = false, bool SP2 = false>
; __device__ __forceinline__ void gemm_phase(PG8_LAS unsigned char* lds, const Gemm g, const Sched& S, const Epi& E) {
;     ...
;         for (int t = 0; t < nt; t += 2) {
;             const bool last = (t == nt - 2);
;             const char* a1 = cA + (size_t)(t + 1) * kstep;
;     ...
; #pragma unroll
;         for (int a = 0; a < 2; ++a)
; #pragma unroll
;             for (int b = 0; b < 2; ++b)
; #pragma unroll
;                 for (int m = 0; m < 4; ++m)
; #pragma unroll
;                     for (int n = 0; n < 2; ++n) acc[a][b][m][n] = (f32x4){0.f, 0.f, 0.f, 0.f};
.LBB0_2384:
	s_andn2_b64 vcc, exec, s[24:25]
	s_waitcnt vmcnt(0)
	s_waitcnt lgkmcnt(0)
	s_cbranch_vccnz .LBB0_2387
	s_add_u32 s30, s30, 0x80
	s_addc_u32 s31, s31, 0
	s_add_u32 s61, s34, 0x100
	v_mov_b32_e32 v0, 0
	s_addc_u32 s62, s35, 0
	s_mov_b32 s34, 0
	v_mov_b32_e32 v1, v0
	v_mov_b32_e32 v2, v0
	v_mov_b32_e32 v3, v0
	v_mov_b32_e32 v4, v0
	v_mov_b32_e32 v5, v0
	v_mov_b32_e32 v6, v0
	v_mov_b32_e32 v7, v0
	v_mov_b32_e32 v16, v0
	v_mov_b32_e32 v17, v0
	v_mov_b32_e32 v18, v0
	v_mov_b32_e32 v19, v0
	v_mov_b32_e32 v20, v0
	v_mov_b32_e32 v21, v0
	v_mov_b32_e32 v22, v0
	v_mov_b32_e32 v23, v0
	v_mov_b32_e32 v32, v0
	v_mov_b32_e32 v33, v0
	v_mov_b32_e32 v34, v0
	v_mov_b32_e32 v35, v0
	v_mov_b32_e32 v36, v0
	v_mov_b32_e32 v37, v0
	v_mov_b32_e32 v38, v0
	v_mov_b32_e32 v39, v0
	v_mov_b32_e32 v48, v0
	v_mov_b32_e32 v49, v0
	v_mov_b32_e32 v50, v0
	v_mov_b32_e32 v51, v0
	v_mov_b32_e32 v52, v0
	v_mov_b32_e32 v53, v0
	v_mov_b32_e32 v54, v0
	v_mov_b32_e32 v55, v0
	v_mov_b32_e32 v8, v0
	v_mov_b32_e32 v9, v0
	v_mov_b32_e32 v10, v0
	v_mov_b32_e32 v11, v0
	v_mov_b32_e32 v12, v0
	v_mov_b32_e32 v13, v0
	v_mov_b32_e32 v14, v0
	v_mov_b32_e32 v15, v0
	v_mov_b32_e32 v24, v0
	v_mov_b32_e32 v25, v0
	v_mov_b32_e32 v26, v0
	v_mov_b32_e32 v27, v0
	v_mov_b32_e32 v28, v0
	v_mov_b32_e32 v29, v0
	v_mov_b32_e32 v30, v0
	v_mov_b32_e32 v31, v0
	v_mov_b32_e32 v40, v0
	v_mov_b32_e32 v41, v0
	v_mov_b32_e32 v42, v0
	v_mov_b32_e32 v43, v0
	v_mov_b32_e32 v44, v0
	v_mov_b32_e32 v45, v0
	v_mov_b32_e32 v46, v0
	v_mov_b32_e32 v47, v0
	v_mov_b32_e32 v56, v0
	v_mov_b32_e32 v57, v0
	v_mov_b32_e32 v58, v0
	v_mov_b32_e32 v59, v0
	v_mov_b32_e32 v60, v0
	v_mov_b32_e32 v61, v0
	v_mov_b32_e32 v62, v0
	v_mov_b32_e32 v63, v0
	v_mov_b32_e32 v64, v0
	v_mov_b32_e32 v65, v0
	v_mov_b32_e32 v66, v0
	v_mov_b32_e32 v67, v0
	v_mov_b32_e32 v68, v0
	v_mov_b32_e32 v69, v0
	v_mov_b32_e32 v70, v0
	v_mov_b32_e32 v71, v0
	v_mov_b32_e32 v80, v0
	v_mov_b32_e32 v81, v0
	v_mov_b32_e32 v82, v0
	v_mov_b32_e32 v83, v0
	v_mov_b32_e32 v84, v0
	v_mov_b32_e32 v85, v0
	v_mov_b32_e32 v86, v0
	v_mov_b32_e32 v87, v0
	v_mov_b32_e32 v96, v0
	v_mov_b32_e32 v97, v0
	v_mov_b32_e32 v98, v0
	v_mov_b32_e32 v99, v0
	v_mov_b32_e32 v100, v0
	v_mov_b32_e32 v101, v0
	v_mov_b32_e32 v102, v0
	v_mov_b32_e32 v103, v0
	v_mov_b32_e32 v112, v0
	v_mov_b32_e32 v113, v0
	v_mov_b32_e32 v114, v0
	v_mov_b32_e32 v115, v0
	v_mov_b32_e32 v116, v0
	v_mov_b32_e32 v117, v0
	v_mov_b32_e32 v118, v0
	v_mov_b32_e32 v119, v0
	v_mov_b32_e32 v72, v0
	v_mov_b32_e32 v73, v0
	v_mov_b32_e32 v74, v0
	v_mov_b32_e32 v75, v0
	v_mov_b32_e32 v76, v0
	v_mov_b32_e32 v77, v0
	v_mov_b32_e32 v78, v0
	v_mov_b32_e32 v79, v0
	v_mov_b32_e32 v88, v0
	v_mov_b32_e32 v89, v0
	v_mov_b32_e32 v90, v0
	v_mov_b32_e32 v91, v0
	v_mov_b32_e32 v92, v0
	v_mov_b32_e32 v93, v0
	v_mov_b32_e32 v94, v0
	v_mov_b32_e32 v95, v0
	v_mov_b32_e32 v104, v0
	v_mov_b32_e32 v105, v0
	v_mov_b32_e32 v106, v0
	v_mov_b32_e32 v107, v0
	v_mov_b32_e32 v108, v0
	v_mov_b32_e32 v109, v0
	v_mov_b32_e32 v110, v0
	v_mov_b32_e32 v111, v0
	v_mov_b32_e32 v120, v0
	v_mov_b32_e32 v121, v0
	v_mov_b32_e32 v122, v0
	v_mov_b32_e32 v123, v0
	v_mov_b32_e32 v124, v0
	v_mov_b32_e32 v125, v0
	v_mov_b32_e32 v126, v0
	v_mov_b32_e32 v127, v0

; template <class Epi, class Sched, bool ALIGN_EPI = false, bool SP2 = false>
; __device__ __forceinline__ void gemm_phase(PG8_LAS unsigned char* lds, const Gemm g, const Sched& S, const Epi& E) {
;     ...
;         for (int t = 0; t < nt; t += 2) {
;             const bool last = (t == nt - 2);
;             const char* a1 = cA + (size_t)(t + 1) * kstep;
;     ...
; #pragma unroll
;         for (int a = 0; a < 2; ++a)
; #pragma unroll
;             for (int b = 0; b < 2; ++b)
; #pragma unroll
;                 for (int m = 0; m < 4; ++m)
; #pragma unroll
;                     for (int n = 0; n < 2; ++n) acc[a][b][m][n] = (f32x4){0.f, 0.f, 0.f, 0.f};
.LBB0_2479:
	s_andn2_b64 vcc, exec, s[20:21]
	s_waitcnt vmcnt(0)
	s_cbranch_vccnz .LBB0_2482
	s_add_u32 s26, s26, 0x80
	s_addc_u32 s27, s27, 0
	s_add_u32 s60, s28, 0x100
	v_mov_b32_e32 v8, 0
	s_addc_u32 s61, s29, 0
	s_mov_b32 s28, 0
	v_mov_b32_e32 v9, v8
	v_mov_b32_e32 v10, v8
	v_mov_b32_e32 v11, v8
	v_mov_b32_e32 v12, v8
	v_mov_b32_e32 v13, v8
	v_mov_b32_e32 v14, v8
	v_mov_b32_e32 v15, v8
	v_mov_b32_e32 v24, v8
	v_mov_b32_e32 v25, v8
	v_mov_b32_e32 v26, v8
	v_mov_b32_e32 v27, v8
	v_mov_b32_e32 v28, v8
	v_mov_b32_e32 v29, v8
	v_mov_b32_e32 v30, v8
	v_mov_b32_e32 v31, v8
	v_mov_b32_e32 v40, v8
	v_mov_b32_e32 v41, v8
	v_mov_b32_e32 v42, v8
	v_mov_b32_e32 v43, v8
	v_mov_b32_e32 v44, v8
	v_mov_b32_e32 v45, v8
	v_mov_b32_e32 v46, v8
	v_mov_b32_e32 v47, v8
	v_mov_b32_e32 v56, v8
	v_mov_b32_e32 v57, v8
	v_mov_b32_e32 v58, v8
	v_mov_b32_e32 v59, v8
	v_mov_b32_e32 v60, v8
	v_mov_b32_e32 v61, v8
	v_mov_b32_e32 v62, v8
	v_mov_b32_e32 v63, v8
	v_mov_b32_e32 v0, v8
	v_mov_b32_e32 v1, v8
	v_mov_b32_e32 v2, v8
	v_mov_b32_e32 v3, v8
	v_mov_b32_e32 v4, v8
	v_mov_b32_e32 v5, v8
	v_mov_b32_e32 v6, v8
	v_mov_b32_e32 v7, v8
	v_mov_b32_e32 v16, v8
	v_mov_b32_e32 v17, v8
	v_mov_b32_e32 v18, v8
	v_mov_b32_e32 v19, v8
	v_mov_b32_e32 v20, v8
	v_mov_b32_e32 v21, v8
	v_mov_b32_e32 v22, v8
	v_mov_b32_e32 v23, v8
	v_mov_b32_e32 v32, v8
	v_mov_b32_e32 v33, v8
	v_mov_b32_e32 v34, v8
	v_mov_b32_e32 v35, v8
	v_mov_b32_e32 v36, v8
	v_mov_b32_e32 v37, v8
	v_mov_b32_e32 v38, v8
	v_mov_b32_e32 v39, v8
	v_mov_b32_e32 v48, v8
	v_mov_b32_e32 v49, v8
	v_mov_b32_e32 v50, v8
	v_mov_b32_e32 v51, v8
	v_mov_b32_e32 v52, v8
	v_mov_b32_e32 v53, v8
	v_mov_b32_e32 v54, v8
	v_mov_b32_e32 v55, v8
	v_mov_b32_e32 v72, v8
	v_mov_b32_e32 v73, v8
	v_mov_b32_e32 v74, v8
	v_mov_b32_e32 v75, v8
	v_mov_b32_e32 v76, v8
	v_mov_b32_e32 v77, v8
	v_mov_b32_e32 v78, v8
	v_mov_b32_e32 v79, v8
	v_mov_b32_e32 v88, v8
	v_mov_b32_e32 v89, v8
	v_mov_b32_e32 v90, v8
	v_mov_b32_e32 v91, v8
	v_mov_b32_e32 v92, v8
	v_mov_b32_e32 v93, v8
	v_mov_b32_e32 v94, v8
	v_mov_b32_e32 v95, v8
	v_mov_b32_e32 v104, v8
	v_mov_b32_e32 v105, v8
	v_mov_b32_e32 v106, v8
	v_mov_b32_e32 v107, v8
	v_mov_b32_e32 v108, v8
	v_mov_b32_e32 v109, v8
	v_mov_b32_e32 v110, v8
	v_mov_b32_e32 v111, v8
	v_mov_b32_e32 v120, v8
	v_mov_b32_e32 v121, v8
	v_mov_b32_e32 v122, v8
	v_mov_b32_e32 v123, v8
	v_mov_b32_e32 v124, v8
	v_mov_b32_e32 v125, v8
	v_mov_b32_e32 v126, v8
	v_mov_b32_e32 v127, v8
	v_mov_b32_e32 v64, v8
	v_mov_b32_e32 v65, v8
	v_mov_b32_e32 v66, v8
	v_mov_b32_e32 v67, v8
	v_mov_b32_e32 v68, v8
	v_mov_b32_e32 v69, v8
	v_mov_b32_e32 v70, v8
	v_mov_b32_e32 v71, v8
	v_mov_b32_e32 v80, v8
	v_mov_b32_e32 v81, v8
	v_mov_b32_e32 v82, v8
	v_mov_b32_e32 v83, v8
	v_mov_b32_e32 v84, v8
	v_mov_b32_e32 v85, v8
	v_mov_b32_e32 v86, v8
	v_mov_b32_e32 v87, v8
	v_mov_b32_e32 v96, v8
	v_mov_b32_e32 v97, v8
	v_mov_b32_e32 v98, v8
	v_mov_b32_e32 v99, v8
	v_mov_b32_e32 v100, v8
	v_mov_b32_e32 v101, v8
	v_mov_b32_e32 v102, v8
	v_mov_b32_e32 v103, v8
	v_mov_b32_e32 v112, v8
	v_mov_b32_e32 v113, v8
	v_mov_b32_e32 v114, v8
	v_mov_b32_e32 v115, v8
	v_mov_b32_e32 v116, v8
	v_mov_b32_e32 v117, v8
	v_mov_b32_e32 v118, v8
	v_mov_b32_e32 v119, v8

; template <class Epi, class Sched, bool ALIGN_EPI = false, bool SP2 = false>
; __device__ __forceinline__ void gemm_phase(PG8_LAS unsigned char* lds, const Gemm g, const Sched& S, const Epi& E) {
;     ...
;         for (int t = 0; t < nt; t += 2) {
;             const bool last = (t == nt - 2);
;             const char* a1 = cA + (size_t)(t + 1) * kstep;
;     ...
; #pragma unroll
;         for (int a = 0; a < 2; ++a)
; #pragma unroll
;             for (int b = 0; b < 2; ++b)
; #pragma unroll
;                 for (int m = 0; m < 4; ++m)
; #pragma unroll
;                     for (int n = 0; n < 2; ++n) acc[a][b][m][n] = (f32x4){0.f, 0.f, 0.f, 0.f};
.LBB0_2573:
	v_mov_b32_e32 v151, 0
	s_andn2_b64 vcc, exec, s[24:25]
	v_mov_b32_e32 v150, 0
	v_mov_b32_e32 v155, 0
	v_mov_b32_e32 v154, 0
	v_mov_b32_e32 v153, 0
	v_mov_b32_e32 v152, 0
	v_mov_b32_e32 v149, 0
	v_mov_b32_e32 v148, 0
	s_waitcnt vmcnt(0)
	v_mov_b32_e32 v145, 0
	v_mov_b32_e32 v144, 0
	v_mov_b32_e32 v147, 0
	v_mov_b32_e32 v146, 0
	s_waitcnt lgkmcnt(0)
	s_cbranch_vccnz .LBB0_2577
	s_add_u32 s30, s30, 0x80
	s_addc_u32 s31, s31, 0
	s_add_u32 s61, s34, 0x100
	v_mov_b32_e32 v0, 0
	s_addc_u32 s62, s35, 0
	s_mov_b32 s34, 0
	v_mov_b32_e32 v1, v0
	v_mov_b32_e32 v2, v0
	v_mov_b32_e32 v3, v0
	v_mov_b32_e32 v4, v0
	v_mov_b32_e32 v5, v0
	v_mov_b32_e32 v6, v0
	v_mov_b32_e32 v7, v0
	v_mov_b32_e32 v8, v0
	v_mov_b32_e32 v9, v0
	v_mov_b32_e32 v10, v0
	v_mov_b32_e32 v11, v0
	v_mov_b32_e32 v12, v0
	v_mov_b32_e32 v13, v0
	v_mov_b32_e32 v14, v0
	v_mov_b32_e32 v15, v0
	v_mov_b32_e32 v20, v0
	v_mov_b32_e32 v21, v0
	v_mov_b32_e32 v22, v0
	v_mov_b32_e32 v23, v0
	v_mov_b32_e32 v28, v0
	v_mov_b32_e32 v29, v0
	v_mov_b32_e32 v30, v0
	v_mov_b32_e32 v31, v0
	v_mov_b32_e32 v36, v0
	v_mov_b32_e32 v37, v0
	v_mov_b32_e32 v38, v0
	v_mov_b32_e32 v39, v0
	v_mov_b32_e32 v44, v0
	v_mov_b32_e32 v45, v0
	v_mov_b32_e32 v46, v0
	v_mov_b32_e32 v47, v0
	v_mov_b32_e32 v16, v0
	v_mov_b32_e32 v17, v0
	v_mov_b32_e32 v18, v0
	v_mov_b32_e32 v19, v0
	v_mov_b32_e32 v24, v0
	v_mov_b32_e32 v25, v0
	v_mov_b32_e32 v26, v0
	v_mov_b32_e32 v27, v0
	v_mov_b32_e32 v32, v0
	v_mov_b32_e32 v33, v0
	v_mov_b32_e32 v34, v0
	v_mov_b32_e32 v35, v0
	v_mov_b32_e32 v40, v0
	v_mov_b32_e32 v41, v0
	v_mov_b32_e32 v42, v0
	v_mov_b32_e32 v43, v0
	v_mov_b32_e32 v48, v0
	v_mov_b32_e32 v49, v0
	v_mov_b32_e32 v50, v0
	v_mov_b32_e32 v51, v0
	v_mov_b32_e32 v52, v0
	v_mov_b32_e32 v53, v0
	v_mov_b32_e32 v54, v0
	v_mov_b32_e32 v55, v0
	v_mov_b32_e32 v56, v0
	v_mov_b32_e32 v57, v0
	v_mov_b32_e32 v58, v0
	v_mov_b32_e32 v59, v0
	v_mov_b32_e32 v60, v0
	v_mov_b32_e32 v61, v0
	v_mov_b32_e32 v62, v0
	v_mov_b32_e32 v63, v0
	v_mov_b32_e32 v64, v0
	v_mov_b32_e32 v65, v0
	v_mov_b32_e32 v66, v0
	v_mov_b32_e32 v67, v0
	v_mov_b32_e32 v68, v0
	v_mov_b32_e32 v69, v0
	v_mov_b32_e32 v70, v0
	v_mov_b32_e32 v71, v0
	v_mov_b32_e32 v72, v0
	v_mov_b32_e32 v73, v0
	v_mov_b32_e32 v74, v0
	v_mov_b32_e32 v75, v0
	v_mov_b32_e32 v76, v0
	v_mov_b32_e32 v77, v0
	v_mov_b32_e32 v78, v0
	v_mov_b32_e32 v79, v0
	v_mov_b32_e32 v84, v0
	v_mov_b32_e32 v85, v0
	v_mov_b32_e32 v86, v0
	v_mov_b32_e32 v87, v0
	v_mov_b32_e32 v92, v0
	v_mov_b32_e32 v93, v0
	v_mov_b32_e32 v94, v0
	v_mov_b32_e32 v95, v0
	v_mov_b32_e32 v100, v0
	v_mov_b32_e32 v101, v0
	v_mov_b32_e32 v102, v0
	v_mov_b32_e32 v103, v0
	v_mov_b32_e32 v108, v0
	v_mov_b32_e32 v109, v0
	v_mov_b32_e32 v110, v0
	v_mov_b32_e32 v111, v0
	v_mov_b32_e32 v80, v0
	v_mov_b32_e32 v81, v0
	v_mov_b32_e32 v82, v0
	v_mov_b32_e32 v83, v0
	v_mov_b32_e32 v88, v0
	v_mov_b32_e32 v89, v0
	v_mov_b32_e32 v90, v0
	v_mov_b32_e32 v91, v0
	v_mov_b32_e32 v96, v0
	v_mov_b32_e32 v97, v0
	v_mov_b32_e32 v98, v0
	v_mov_b32_e32 v99, v0
	v_mov_b32_e32 v104, v0
	v_mov_b32_e32 v105, v0
	v_mov_b32_e32 v106, v0
	v_mov_b32_e32 v107, v0
	v_mov_b32_e32 v112, v0
	v_mov_b32_e32 v113, v0
	v_mov_b32_e32 v114, v0
	v_mov_b32_e32 v115, v0
	v_mov_b32_e32 v116, v0
	v_mov_b32_e32 v117, v0
	v_mov_b32_e32 v118, v0
	v_mov_b32_e32 v119, v0
	v_mov_b32_e32 v120, v0
	v_mov_b32_e32 v121, v0
	v_mov_b32_e32 v122, v0
	v_mov_b32_e32 v123, v0
	v_mov_b32_e32 v124, v0
	v_mov_b32_e32 v125, v0
	v_mov_b32_e32 v126, v0
	v_mov_b32_e32 v127, v0
